# combo3 + attention: QK^T ds_read ladders pipelined one step ahead (two loop copies) + Q tile loads issued together with counted waits instead of 8 serialized round trips
# speedup vs baseline: 1.0024x; 1.0024x over previous
.LBB0_407:
	s_ashr_i32 s10, s49, 7
	s_ashr_i32 s11, s10, 31
	s_lshl_b32 s8, s49, 6
	s_lshl_b64 s[14:15], s[10:11], 11
	s_and_b32 s51, s8, 0x7c0
	s_or_b32 s14, s14, s51
	s_mul_i32 s8, s15, 0x6800
	s_mul_hi_u32 s9, s14, 0x6800
	s_bfe_u32 s28, s49, 0x20005
	s_add_i32 s9, s9, s8
	s_mul_i32 s8, s14, 0x6800
	s_add_u32 s8, s16, s8
	s_addc_u32 s9, s17, s9
	s_lshl_b32 s11, s28, 10
	s_add_u32 s8, s8, s11
	s_addc_u32 s9, s9, 0
	s_mul_hi_i32 s11, s10, 0x3400000
	s_mul_i32 s10, s10, 0x3400000
	s_add_u32 s10, s16, s10
	s_addc_u32 s11, s17, s11
	s_lshl_b32 s12, s28, 8
	s_add_u32 s12, s10, s12
	s_addc_u32 s13, s11, 0
	s_add_u32 s10, s12, 0x1000
	s_addc_u32 s11, s13, 0
	s_mov_b32 s20, -1
	s_add_u32 s12, s12, 0x1400
	s_addc_u32 s13, s13, 0
	v_mbcnt_lo_u32_b32 v0, s20, 0
	v_mbcnt_hi_u32_b32 v0, s20, v0
	s_add_i32 s20, s51, 0xffffff80
	s_lshr_b32 s20, s20, 6
	s_cmpk_gt_u32 s51, 0x80
	s_cselect_b32 s20, s20, 0
	s_add_i32 s21, s51, 0xbf
	s_lshr_b32 s21, s21, 6
	s_min_u32 s27, s21, 31
	s_add_i32 s50, s27, 1
	s_lshl_b32 s21, s28, 4
	s_add_u32 s34, s42, s21
	v_add_u32_e32 v174, s76, v0
	s_addc_u32 s35, s43, 0
	v_mov_b64_e32 v[2:3], s[34:35]
	v_ashrrev_i32_e32 v182, 4, v174
	global_load_dword v67, v[2:3], off
	v_and_b32_e32 v3, 0xfffff0, v182
	v_lshlrev_b32_e32 v4, 1, v182
	v_lshlrev_b32_e32 v0, 3, v174
	v_and_or_b32 v3, v4, 8, v3
	v_lshrrev_b32_e32 v3, 1, v3
	v_bfe_u32 v5, v0, 5, 2
	v_and_b32_e32 v2, 0x78, v0
	v_or_b32_e32 v0, v3, v5
	v_lshrrev_b32_e32 v4, 1, v182
	v_lshlrev_b32_e32 v3, 9, v0
	v_and_b32_e32 v0, 3, v182
	v_and_or_b32 v0, v4, 4, v0
	v_lshlrev_b32_e32 v10, 6, v0
	v_lshlrev_b32_e32 v0, 1, v2
	v_add_u32_e32 v2, 32, v182
	v_and_b32_e32 v4, 0xfffff0, v2
	v_lshlrev_b32_e32 v6, 1, v2
	v_and_or_b32 v4, v6, 8, v4
	v_lshrrev_b32_e32 v4, 1, v4
	v_or_b32_e32 v4, v4, v5
	v_and_b32_e32 v11, 48, v0
	v_lshlrev_b32_e32 v4, 9, v4
	s_lshl_b32 s58, s20, 6
	v_or3_b32 v12, v4, v10, v11
	v_add_u32_e32 v8, s58, v182
	v_mov_b64_e32 v[4:5], s[12:13]
	v_add_u32_e32 v9, s58, v2
	v_mad_i64_i32 v[6:7], s[34:35], v8, s72, v[4:5]
	v_mad_i64_i32 v[4:5], s[34:35], v9, s72, v[4:5]
	v_lshl_add_u64 v[6:7], v[6:7], 0, v[0:1]
	v_lshl_add_u64 v[4:5], v[4:5], 0, v[0:1]
	global_load_dwordx4 v[50:53], v[6:7], off
	global_load_dwordx4 v[54:57], v[4:5], off
	v_mov_b64_e32 v[4:5], s[10:11]
	v_mad_i64_i32 v[6:7], s[34:35], v8, s72, v[4:5]
	v_mad_i64_i32 v[4:5], s[34:35], v9, s72, v[4:5]
	v_and_b32_e32 v176, 31, v174
	v_lshl_add_u64 v[6:7], v[6:7], 0, v[0:1]
	v_lshl_add_u64 v[4:5], v[4:5], 0, v[0:1]
	global_load_dwordx4 v[58:61], v[6:7], off
	global_load_dwordx4 v[62:65], v[4:5], off
	v_or_b32_e32 v4, s60, v176
	v_mul_u32_u24_e32 v4, 0x3400, v4
	v_lshlrev_b32_e32 v4, 1, v4
	v_mov_b32_e32 v5, v1
	v_bfe_u32 v175, v174, 5, 1
	v_lshl_add_u64 v[4:5], s[8:9], 0, v[4:5]
	v_lshl_add_u64 v[4:5], s[74:75], 1, v[4:5]
	v_lshlrev_b32_e32 v170, 4, v175
	v_mov_b32_e32 v171, v1
	v_lshl_add_u64 v[8:9], v[4:5], 0, v[170:171]
	global_load_dwordx4 v[4:7], v[8:9], off
	global_load_dwordx4 v[68:71], v[8:9], off offset:32
	global_load_dwordx4 v[72:75], v[8:9], off offset:64
	global_load_dwordx4 v[76:79], v[8:9], off offset:96
	global_load_dwordx4 v[80:83], v[8:9], off offset:128
	global_load_dwordx4 v[84:87], v[8:9], off offset:160
	global_load_dwordx4 v[88:91], v[8:9], off offset:192
	global_load_dwordx4 v[92:95], v[8:9], off offset:224
	v_and_b32_e32 v177, 63, v174
	v_lshlrev_b32_e32 v66, 4, v177
	v_add_u32_e32 v180, s62, v66
	v_and_b32_e32 v13, 0x70, v174
	v_or3_b32 v3, v3, v10, v11
	s_sub_i32 s54, s50, s20
	v_add_u32_e32 v186, 0, v3
	v_add_u32_e32 v187, 0, v12
	s_waitcnt vmcnt(7)
	ds_write_b128 v180, v[4:7]
	s_waitcnt vmcnt(6)
	ds_write_b128 v180, v[68:71] offset:1024
	s_waitcnt vmcnt(5)
	ds_write_b128 v180, v[72:75] offset:2048
	s_waitcnt vmcnt(4)
	ds_write_b128 v180, v[76:79] offset:3072
	s_waitcnt vmcnt(3)
	ds_write_b128 v180, v[80:83] offset:4096
	s_waitcnt vmcnt(2)
	ds_write_b128 v180, v[84:87] offset:5120
	s_waitcnt vmcnt(1)
	ds_write_b128 v180, v[88:91] offset:6144
	s_waitcnt vmcnt(0)
	ds_write_b128 v180, v[92:95] offset:7168
	v_lshlrev_b32_e32 v4, 8, v182
	s_waitcnt vmcnt(0)
	v_bitop3_b32 v4, v0, v4, v13 bitop3:0xde
	v_add_u32_e32 v185, 0, v4
	ds_write_b128 v185, v[58:61] offset:32768
	ds_write_b128 v185, v[62:65] offset:40960
	s_waitcnt lgkmcnt(0)
	s_barrier
	ds_write_b128 v186, v[50:53]
	ds_write_b128 v187, v[54:57]
	s_cmp_gt_i32 s54, 1
	s_cselect_b64 s[20:21], -1, 0
	s_cmp_lt_i32 s54, 2
	s_cbranch_scc1 .LBB0_409
	s_add_i32 s34, s58, 64
	v_add_u32_e32 v8, s34, v182
	v_mov_b64_e32 v[4:5], s[12:13]
	v_add_u32_e32 v9, s34, v2
	v_mad_i64_i32 v[6:7], s[8:9], v8, s72, v[4:5]
	v_mad_i64_i32 v[2:3], s[8:9], v9, s72, v[4:5]
	v_lshl_add_u64 v[6:7], v[6:7], 0, v[0:1]
	v_lshl_add_u64 v[2:3], v[2:3], 0, v[0:1]
	global_load_dwordx4 v[50:53], v[6:7], off
	global_load_dwordx4 v[54:57], v[2:3], off
	v_mov_b64_e32 v[2:3], s[10:11]
	v_mad_i64_i32 v[4:5], s[8:9], v8, s72, v[2:3]
	v_lshl_add_u64 v[4:5], v[4:5], 0, v[0:1]
	v_mad_i64_i32 v[2:3], s[8:9], v9, s72, v[2:3]
	v_lshl_add_u64 v[2:3], v[2:3], 0, v[0:1]
	global_load_dwordx4 v[58:61], v[4:5], off
	global_load_dwordx4 v[62:65], v[2:3], off

.LBB0_419:
	s_add_i32 s12, s58, 64
	s_cmp_gt_u32 s12, s52
	s_cselect_b64 s[10:11], -1, 0
	s_add_i32 s13, s58, 0x7f
	s_cmp_lt_i32 s13, s53
	s_cselect_b64 s[20:21], -1, 0
	s_or_b64 s[10:11], s[10:11], s[20:21]
	s_and_b64 vcc, exec, s[10:11]
	s_cbranch_vccnz .LBB0_421
	s_waitcnt lgkmcnt(0)
	ds_read_b128 v[2:5], v189 offset:49152
	ds_read_b128 v[6:9], v180 offset:0
	ds_read_b128 v[10:13], v189 offset:57344
	ds_read_b128 v[36:39], v190 offset:49152
	ds_read_b128 v[44:47], v180 offset:1024
	ds_read_b128 v[40:43], v190 offset:57344
	s_waitcnt lgkmcnt(3)
	v_mfma_f32_32x32x16_bf16 v[118:133], v[2:5], v[6:9], 0
	v_mfma_f32_32x32x16_bf16 v[102:117], v[10:13], v[6:9], 0
	ds_read_b128 v[2:5], v191 offset:49152
	ds_read_b128 v[6:9], v180 offset:2048
	ds_read_b128 v[10:13], v191 offset:57344
	s_waitcnt lgkmcnt(3)
	v_mfma_f32_32x32x16_bf16 v[118:133], v[36:39], v[44:47], v[118:133]
	v_mfma_f32_32x32x16_bf16 v[102:117], v[40:43], v[44:47], v[102:117]
	ds_read_b128 v[36:39], v196 offset:49152
	ds_read_b128 v[44:47], v180 offset:3072
	ds_read_b128 v[40:43], v196 offset:57344
	s_waitcnt lgkmcnt(3)
	v_mfma_f32_32x32x16_bf16 v[118:133], v[2:5], v[6:9], v[118:133]
	v_mfma_f32_32x32x16_bf16 v[102:117], v[10:13], v[6:9], v[102:117]
	ds_read_b128 v[2:5], v189 offset:49280
	ds_read_b128 v[6:9], v180 offset:4096
	ds_read_b128 v[10:13], v189 offset:57472
	s_waitcnt lgkmcnt(3)
	v_mfma_f32_32x32x16_bf16 v[118:133], v[36:39], v[44:47], v[118:133]
	v_mfma_f32_32x32x16_bf16 v[102:117], v[40:43], v[44:47], v[102:117]
	ds_read_b128 v[36:39], v190 offset:49280
	ds_read_b128 v[44:47], v180 offset:5120
	ds_read_b128 v[40:43], v190 offset:57472
	s_waitcnt lgkmcnt(3)
	v_mfma_f32_32x32x16_bf16 v[118:133], v[2:5], v[6:9], v[118:133]
	v_mfma_f32_32x32x16_bf16 v[102:117], v[10:13], v[6:9], v[102:117]
	ds_read_b128 v[2:5], v191 offset:49280
	ds_read_b128 v[6:9], v180 offset:6144
	ds_read_b128 v[10:13], v191 offset:57472
	s_waitcnt lgkmcnt(3)
	v_mfma_f32_32x32x16_bf16 v[118:133], v[36:39], v[44:47], v[118:133]
	v_mfma_f32_32x32x16_bf16 v[102:117], v[40:43], v[44:47], v[102:117]
	ds_read_b128 v[36:39], v196 offset:49280
	ds_read_b128 v[44:47], v180 offset:7168
	ds_read_b128 v[40:43], v196 offset:57472
	s_waitcnt lgkmcnt(3)
	v_mfma_f32_32x32x16_bf16 v[118:133], v[2:5], v[6:9], v[118:133]
	v_mfma_f32_32x32x16_bf16 v[102:117], v[10:13], v[6:9], v[102:117]
	s_waitcnt lgkmcnt(0)
	v_mfma_f32_32x32x16_bf16 v[118:133], v[36:39], v[44:47], v[118:133]
	v_mfma_f32_32x32x16_bf16 v[102:117], v[40:43], v[44:47], v[102:117]
	s_branch .LBB0_422

.LBB0_431:
	v_cndmask_b32_e64 v198, v35, v166, s[12:13]
	v_mul_f32_e32 v166, 0xbe0293ee, v198
	v_fmamk_f32 v35, v118, 0x3e0293ee, v166
	v_fmamk_f32 v36, v119, 0x3e0293ee, v166
	v_fmamk_f32 v37, v120, 0x3e0293ee, v166
	v_fmamk_f32 v38, v121, 0x3e0293ee, v166
	v_fmamk_f32 v39, v122, 0x3e0293ee, v166
	v_fmamk_f32 v40, v123, 0x3e0293ee, v166
	v_fmamk_f32 v41, v124, 0x3e0293ee, v166
	v_fmamk_f32 v42, v125, 0x3e0293ee, v166
	v_fmamk_f32 v43, v126, 0x3e0293ee, v166
	v_fmamk_f32 v44, v127, 0x3e0293ee, v166
	v_fmamk_f32 v45, v128, 0x3e0293ee, v166
	v_fmamk_f32 v46, v129, 0x3e0293ee, v166
	v_fmamk_f32 v47, v130, 0x3e0293ee, v166
	v_fmamk_f32 v48, v131, 0x3e0293ee, v166
	v_fmamk_f32 v49, v132, 0x3e0293ee, v166
	v_fmamk_f32 v130, v133, 0x3e0293ee, v166
	v_fmamk_f32 v118, v102, 0x3e0293ee, v166
	v_fmamk_f32 v119, v103, 0x3e0293ee, v166
	v_fmamk_f32 v120, v104, 0x3e0293ee, v166
	v_fmamk_f32 v121, v105, 0x3e0293ee, v166
	v_fmamk_f32 v122, v106, 0x3e0293ee, v166
	v_fmamk_f32 v123, v107, 0x3e0293ee, v166
	v_fmamk_f32 v124, v108, 0x3e0293ee, v166
	v_fmamk_f32 v125, v109, 0x3e0293ee, v166
	v_fmamk_f32 v126, v110, 0x3e0293ee, v166
	v_fmamk_f32 v127, v111, 0x3e0293ee, v166
	v_fmamk_f32 v128, v112, 0x3e0293ee, v166
	v_fmamk_f32 v129, v113, 0x3e0293ee, v166
	v_exp_f32_e32 v98, v35
	v_exp_f32_e32 v99, v36
	v_exp_f32_e32 v100, v37
	v_exp_f32_e32 v101, v38
	v_exp_f32_e32 v102, v39
	v_exp_f32_e32 v103, v40
	v_exp_f32_e32 v104, v41
	v_exp_f32_e32 v105, v42
	v_exp_f32_e32 v106, v43
	v_exp_f32_e32 v107, v44
	v_exp_f32_e32 v108, v45
	v_exp_f32_e32 v109, v46
	v_exp_f32_e32 v110, v47
	v_exp_f32_e32 v111, v48
	v_exp_f32_e32 v112, v49
	v_exp_f32_e32 v113, v130
	v_fmamk_f32 v167, v114, 0x3e0293ee, v166
	v_fmamk_f32 v168, v115, 0x3e0293ee, v166
	v_fmamk_f32 v169, v116, 0x3e0293ee, v166
	v_fmac_f32_e32 v166, 0x3e0293ee, v117
	s_add_i32 s59, s58, 0x80
	s_waitcnt lgkmcnt(0)
	s_barrier
	s_cmp_gt_i32 s59, s52
	s_cselect_b64 s[12:13], -1, 0
	s_add_i32 s20, s58, 0xbf
	s_cmp_lt_i32 s20, s53
	s_cselect_b64 s[20:21], -1, 0
	s_or_b64 s[12:13], s[12:13], s[20:21]
	s_and_b64 vcc, exec, s[12:13]
	s_cbranch_vccnz .LBB0_433
	s_waitcnt lgkmcnt(0)
	ds_read_b128 v[36:39], v189 offset:32768
	ds_read_b128 v[40:43], v180 offset:0
	ds_read_b128 v[44:47], v189 offset:40960
	ds_read_b128 v[114:117], v190 offset:32768
	ds_read_b128 v[210:213], v180 offset:1024
	ds_read_b128 v[192:195], v190 offset:40960
	s_waitcnt lgkmcnt(3)
	v_mfma_f32_32x32x16_bf16 v[146:161], v[36:39], v[40:43], 0
	v_mfma_f32_32x32x16_bf16 v[130:145], v[44:47], v[40:43], 0
	ds_read_b128 v[36:39], v191 offset:32768
	ds_read_b128 v[40:43], v180 offset:2048
	ds_read_b128 v[44:47], v191 offset:40960
	s_waitcnt lgkmcnt(3)
	v_mfma_f32_32x32x16_bf16 v[146:161], v[114:117], v[210:213], v[146:161]
	v_mfma_f32_32x32x16_bf16 v[130:145], v[192:195], v[210:213], v[130:145]
	ds_read_b128 v[114:117], v196 offset:32768
	ds_read_b128 v[210:213], v180 offset:3072
	ds_read_b128 v[192:195], v196 offset:40960
	s_waitcnt lgkmcnt(3)
	v_mfma_f32_32x32x16_bf16 v[146:161], v[36:39], v[40:43], v[146:161]
	v_mfma_f32_32x32x16_bf16 v[130:145], v[44:47], v[40:43], v[130:145]
	ds_read_b128 v[36:39], v189 offset:32896
	ds_read_b128 v[40:43], v180 offset:4096
	ds_read_b128 v[44:47], v189 offset:41088
	s_waitcnt lgkmcnt(3)
	v_mfma_f32_32x32x16_bf16 v[146:161], v[114:117], v[210:213], v[146:161]
	v_mfma_f32_32x32x16_bf16 v[130:145], v[192:195], v[210:213], v[130:145]
	ds_read_b128 v[114:117], v190 offset:32896
	ds_read_b128 v[210:213], v180 offset:5120
	ds_read_b128 v[192:195], v190 offset:41088
	s_waitcnt lgkmcnt(3)
	v_mfma_f32_32x32x16_bf16 v[146:161], v[36:39], v[40:43], v[146:161]
	v_mfma_f32_32x32x16_bf16 v[130:145], v[44:47], v[40:43], v[130:145]
	ds_read_b128 v[36:39], v191 offset:32896
	ds_read_b128 v[40:43], v180 offset:6144
	ds_read_b128 v[44:47], v191 offset:41088
	s_waitcnt lgkmcnt(3)
	v_mfma_f32_32x32x16_bf16 v[146:161], v[114:117], v[210:213], v[146:161]
	v_mfma_f32_32x32x16_bf16 v[130:145], v[192:195], v[210:213], v[130:145]
	ds_read_b128 v[114:117], v196 offset:32896
	ds_read_b128 v[210:213], v180 offset:7168
	ds_read_b128 v[192:195], v196 offset:41088
	s_waitcnt lgkmcnt(3)
	v_mfma_f32_32x32x16_bf16 v[146:161], v[36:39], v[40:43], v[146:161]
	v_mfma_f32_32x32x16_bf16 v[130:145], v[44:47], v[40:43], v[130:145]
	s_waitcnt lgkmcnt(0)
	v_mfma_f32_32x32x16_bf16 v[146:161], v[114:117], v[210:213], v[146:161]
	v_mfma_f32_32x32x16_bf16 v[130:145], v[192:195], v[210:213], v[130:145]
	s_branch .LBB0_434
